# row phases: non-temporal hint also on the bf16 residual-stream (x) stores, which are re-read only two GEMM phases later
# speedup vs baseline: 1.0039x; 1.0039x over previous
.Lrw_sxb_A:
	s_lshl_b32 s0, s68, 11
	s_add_u32 s46, s14, s0
	s_addc_u32 s47, s15, 0
	global_store_dwordx2 v161, v[180:181], s[46:47] offset:0 nt
	global_store_dwordx2 v161, v[182:183], s[46:47] offset:512 nt
	global_store_dwordx2 v161, v[184:185], s[46:47] offset:1024 nt
	global_store_dwordx2 v161, v[186:187], s[46:47] offset:1536 nt
